# dilated attention block items cover 16 wave tasks (two per wave back to back): 768 fewer queue rounds per layer in M2
# baseline (speedup 1.0000x reference)
.LBB0_854:
	s_or_b64 exec, exec, s[6:7]
	s_add_i32 s6, s52, 1
	s_cmp_eq_u32 s52, 3
	s_movk_i32 s4, 0x660
	s_cselect_b32 s22, s4, 0xafb
	v_readlane_b32 s4, v249, 4
	s_waitcnt lgkmcnt(0)
	s_barrier
	v_readlane_b32 s5, v249, 5
	s_add_u32 s4, s66, s4
	s_addc_u32 s5, s67, s5
	s_add_u32 s20, s4, 0x100004
	s_addc_u32 s21, s5, 0
	s_add_u32 s4, s66, 0x100400
	s_addc_u32 s5, s67, 0
	v_writelane_b32 v249, s4, 44
	s_lshl_b32 s17, s6, 16
	v_bfe_u32 v2, v203, 4, 2
	v_writelane_b32 v249, s5, 45
	s_add_u32 s4, s66, 0x2870400
	v_writelane_b32 v249, s4, 46
	s_addc_u32 s4, s67, 0
	v_writelane_b32 v249, s4, 47
	s_add_u32 s4, s66, 0x2868400
	v_writelane_b32 v249, s4, 48
	s_addc_u32 s4, s67, 0
	v_writelane_b32 v249, s4, 49
	s_lshl_b32 s4, s6, 21
	v_writelane_b32 v249, s4, 50
	s_add_u32 s4, s66, 0x2768400
	v_writelane_b32 v249, s4, 51
	s_addc_u32 s4, s67, 0
	v_writelane_b32 v249, s4, 52
	s_add_u32 s4, s66, 0x2668400
	v_writelane_b32 v249, s4, 53
	s_addc_u32 s4, s67, 0
	v_writelane_b32 v249, s4, 54
	s_mul_i32 s4, s6, 0x60000
	v_writelane_b32 v249, s4, 55
	s_add_u32 s4, s66, 0x2608400
	v_writelane_b32 v249, s4, 56
	s_addc_u32 s4, s67, 0
	v_writelane_b32 v249, s4, 57
	s_add_u32 s4, s66, 0x408400
	v_writelane_b32 v249, s4, 58
	s_addc_u32 s4, s67, 0
	v_writelane_b32 v249, s4, 59
	s_lshl_b32 s4, s6, 10
	s_mov_b32 s5, s69
	v_writelane_b32 v249, s4, 60
	v_ashrrev_i32_e32 v0, 6, v203
	v_and_b32_e32 v205, 15, v203
	v_writelane_b32 v249, s5, 61
	s_add_u32 s4, s66, 0x1488400
	v_writelane_b32 v249, s4, 62
	s_addc_u32 s4, s67, 0
	v_writelane_b32 v249, s4, 63
	s_mul_i32 s4, s6, 0xb00000
	v_writelane_b32 v248, s4, 0
	s_add_u32 s4, s66, 0xf08400
	v_writelane_b32 v248, s4, 1
	s_addc_u32 s4, s67, 0
	v_lshlrev_b32_e32 v160, 2, v2
	v_writelane_b32 v248, s4, 2
	v_add_u32_e32 v204, 0xffffe500, v0
	v_lshlrev_b32_e32 v0, 3, v2
	v_sub_u32_e32 v2, v160, v205
	s_movk_i32 s4, 0x81
	v_writelane_b32 v249, s6, 8
	v_cmp_gt_u32_e64 s[6:7], s4, v2
	v_add_u32_e32 v4, 1, v2
	s_add_u32 s88, s66, 0xea78400
	v_writelane_b32 v249, s6, 28
	s_addc_u32 s89, s67, 0
	v_and_b32_e32 v3, 63, v203
	v_writelane_b32 v249, s7, 29
	v_cmp_gt_u32_e64 s[6:7], s4, v4
	v_add_u32_e32 v4, 2, v2
	v_or_b32_e32 v206, 0xffffff90, v205
	v_writelane_b32 v249, s6, 21
	v_or_b32_e32 v207, 0xffffffb0, v205
	v_or_b32_e32 v208, 0xffffffd0, v205
	v_writelane_b32 v249, s7, 22
	v_cmp_gt_u32_e64 s[6:7], s4, v4
	v_add_u32_e32 v4, 3, v2
	v_or_b32_e32 v209, -16, v203
	v_writelane_b32 v249, s6, 23
	v_or_b32_e32 v210, 16, v160
	v_lshlrev_b32_e32 v162, 1, v0
	v_writelane_b32 v249, s7, 24
	v_cmp_gt_u32_e64 s[6:7], s4, v4
	v_add_u32_e32 v4, 0x80, v2
	s_nop 0
	v_writelane_b32 v249, s6, 25
	s_nop 1
	v_writelane_b32 v249, s7, 26
	v_cmp_gt_u32_e64 s[6:7], s4, v4
	v_add_u32_e32 v4, 0x82, v2
	s_nop 0
	v_writelane_b32 v249, s6, 15
	s_nop 1
	v_writelane_b32 v249, s7, 16
	v_cmp_lt_u32_e64 s[6:7], 12, v2
	v_add_u32_e32 v2, 0x83, v2
	s_nop 0
	v_writelane_b32 v249, s6, 17
	s_nop 1
	v_writelane_b32 v249, s7, 18
	v_cmp_gt_u32_e64 s[6:7], s4, v4
	v_cmp_gt_u32_e64 s[4:5], s4, v2
	v_lshlrev_b32_e32 v2, 14, v205
	v_writelane_b32 v249, s6, 19
	v_lshlrev_b32_e32 v164, 1, v2
	s_nop 0
	v_writelane_b32 v249, s7, 20
	v_writelane_b32 v249, s4, 9
	s_nop 1
	v_writelane_b32 v249, s5, 10
	s_add_u32 s4, s66, 0xd278400
	s_addc_u32 s5, s67, 0
	v_writelane_b32 v249, s4, 11
	s_nop 1
	v_writelane_b32 v249, s5, 12
	v_cmp_gt_u32_e64 s[4:5], 16, v3
	s_nop 1
	v_writelane_b32 v249, s4, 13
	s_nop 1
	v_writelane_b32 v249, s5, 14
	s_add_u32 s4, s66, 0x108400
	s_addc_u32 s5, s67, 0
	v_writelane_b32 v248, s4, 3
	s_nop 1
	v_writelane_b32 v248, s5, 4
	s_add_u32 s4, s66, 0x3a8400
	v_writelane_b32 v249, s4, 42
	s_addc_u32 s4, s67, 0
	v_writelane_b32 v249, s4, 43
	s_add_u32 s4, s66, 0x348400
	v_writelane_b32 v249, s4, 32
	s_addc_u32 s4, s67, 0
	s_add_u32 s18, s66, 0xa678400
	s_addc_u32 s19, s67, 0
	v_writelane_b32 v249, s4, 33
	s_add_u32 s4, s66, 0xea7c300
	v_writelane_b32 v249, s4, 38
	s_addc_u32 s4, s67, 0
	v_writelane_b32 v249, s4, 40
	s_add_u32 s4, s66, 0xc678400
	v_writelane_b32 v249, s4, 4
	s_addc_u32 s4, s67, 0
	v_writelane_b32 v249, s4, 34
	s_add_u32 s4, s66, 0xea7c600
	v_writelane_b32 v249, s4, 36
	s_addc_u32 s4, s67, 0
	v_writelane_b32 v249, s4, 30
	s_add_u32 s4, s66, 0xcc78400
	v_writelane_b32 v249, s4, 31
	s_addc_u32 s4, s67, 0
	s_add_u32 s86, s66, 0x7678400
	s_addc_u32 s87, s67, 0
	v_writelane_b32 v249, s4, 27
	s_add_u32 s4, s66, 0x8e78400
	s_addc_u32 s5, s67, 0
	s_add_u32 s90, s66, 0x5e78400
	s_addc_u32 s91, s67, 0
	s_add_u32 s6, s66, 0x25da400
	s_addc_u32 s7, s67, 0
	v_writelane_b32 v248, s6, 5
	s_nop 1
	v_writelane_b32 v248, s7, 6
	s_add_u32 s6, s66, 0x288400
	s_addc_u32 s7, s67, 0
	s_add_u32 s15, s66, 0x1c8400
	v_writelane_b32 v249, s6, 6
	s_addc_u32 s23, s67, 0
	s_nop 0
	v_writelane_b32 v249, s7, 7
	s_branch .LBB0_857

.LBB0_861:
	s_or_b64 exec, exec, s[28:29]
	v_mov_b32_e32 v0, s71
	s_waitcnt lgkmcnt(0)
	s_barrier
	ds_read_b32 v0, v0
	s_mov_b64 s[6:7], -1
	s_waitcnt lgkmcnt(0)
	v_cmp_le_i32_e32 vcc, s22, v0
	v_readfirstlane_b32 s24, v0
	s_cbranch_vccnz .LBB0_856
	s_cmpk_gt_i32 s24, 0x5f
	s_cbranch_scc0 .LBB0_1256
	s_cmpk_gt_u32 s24, 0x35f
	s_cbranch_scc0 .LBB0_1057
	s_cmpk_gt_u32 s24, 0x65f
	s_cbranch_scc0 .LBB0_1052
	s_addk_i32 s24, 0x300
	s_cmpk_lt_u32 s24, 0x971
	s_cselect_b32 s25, 0x49b, 0
	s_add_i32 s24, s24, s25
	s_sub_i32 s24, s24, 17
	s_lshl_b32 s25, s24, 3
	s_cmpk_gt_u32 s24, 0xd9b
	s_cbranch_scc0 .LBB0_925
	v_mov_b32_e32 v8, v203
	s_nop 0
	v_readfirstlane_b32 s36, v8
	s_ashr_i32 s10, s36, 6
	s_add_i32 s27, s25, s10
	s_addk_i32 s27, 0x9320
	s_cmpk_gt_i32 s27, 0x2f7
	s_cbranch_scc1 .LBB0_924
	s_mul_i32 s6, s10, 0x2100
	s_add_i32 s26, s6, 0
	v_and_b32_e32 v10, 63, v8
	s_cmp_gt_i32 s27, 47
	s_mov_b64 s[6:7], -1
	s_cbranch_scc0 .LBB0_898
	s_cmpk_gt_u32 s27, 0x5f
	s_cbranch_scc0 .LBB0_895
	s_cmpk_gt_u32 s27, 0x15f
	s_cbranch_scc0 .LBB0_892
	s_cmpk_gt_u32 s27, 0x25f
	s_cbranch_scc0 .LBB0_889
	s_cmpk_gt_u32 s27, 0x267
	s_cbranch_scc0 .LBB0_886
	s_cmpk_gt_u32 s27, 0x26f
	s_cbranch_scc0 .LBB0_883
	s_cmpk_gt_u32 s27, 0x2ef
	s_cbranch_scc0 .LBB0_877
	s_lshl_b32 s6, s24, 9
	s_lshl_b32 s7, s10, 6
	s_add_i32 s6, s6, s7
	s_add_i32 s7, s6, 0xffe40a00
	s_add_i32 s6, s6, 0xffe40c00
	v_or_b32_e32 v0, s7, v10
	v_or_b32_e32 v6, s6, v10
	v_readlane_b32 s6, v248, 5
	v_mov_b32_e32 v2, v1
	v_ashrrev_i32_e32 v7, 31, v6
	v_readlane_b32 s7, v248, 6
	s_mov_b64 s[28:29], 0
	v_mov_b32_e32 v3, v2
	v_mov_b32_e32 v4, v2
	v_mov_b32_e32 v5, v2
	v_lshl_add_u64 v[6:7], v[6:7], 4, s[6:7]
	s_mov_b64 s[10:11], 0x2000

.LBB0_1052:
	s_andn2_b64 vcc, exec, s[6:7]
	s_cbranch_vccnz .LBB0_1056
	v_lshl_add_u32 v0, s24, 3, v204
	s_nop 0
	v_readfirstlane_b32 s6, v0
	s_lshl_b32 s27, s6, 1
.Ldil2_loop:
	s_mov_b32 s6, s27
	s_lshr_b32 s7, s6, 10
	s_and_b32 s6, s6, 0x3ff
	s_lshr_b32 s10, s7, 2
	s_lshl_b32 s10, s10, 1
	s_sub_i32 s11, 10, s10
	s_lshr_b32 s12, s6, s11
	s_lshl_b32 s13, s12, s11
	s_sub_i32 s6, s6, s13
	s_lshl_b32 s13, s6, 4
	s_sub_i32 s28, s13, 0x80
	s_lshl_b32 s29, s63, s10
	s_mul_i32 s30, s12, s63
	s_lshl_b32 s31, s7, 7
	s_add_u32 s34, s88, s31
	s_addc_u32 s35, s89, 0
	s_add_u32 s36, s34, 0x1800
	s_addc_u32 s37, s35, 0
	s_lshl_b32 s40, s7, 21
	s_add_u32 s38, s66, 0xd278400
	s_addc_u32 s39, s67, 0
	s_add_u32 s38, s38, s40
	s_addc_u32 s39, s39, 0
	s_lshr_b32 s41, 0x4000, s10
	s_mul_i32 s41, s41, s12
	s_lshl_b32 s41, s41, 7
	s_add_u32 s38, s38, s41
	s_addc_u32 s39, s39, 0
	v_add_u32_e32 v0, s30, v162
	v_add_u32_e32 v114, s28, v205
	v_add_u32_e32 v144, s13, v205
	v_mad_u32_u24 v182, v144, s29, v0
	global_load_dwordx4 v[2:5], v182, s[36:37] offset:-1536
	global_load_dwordx4 v[6:9], v182, s[36:37] offset:-1472
	v_max_i32_e32 v145, 0, v114
	v_mad_u32_u24 v183, v145, s29, v0
	global_load_dwordx4 v[10:13], v183, s[36:37]
	global_load_dwordx4 v[14:17], v183, s[36:37] offset:64
	v_add_u32_e32 v145, 16, v114
	v_max_i32_e32 v145, 0, v145
	v_mad_u32_u24 v184, v145, s29, v0
	global_load_dwordx4 v[18:21], v184, s[36:37]
	global_load_dwordx4 v[22:25], v184, s[36:37] offset:64
	v_add_u32_e32 v145, 32, v114
	v_max_i32_e32 v145, 0, v145
	v_mad_u32_u24 v185, v145, s29, v0
	global_load_dwordx4 v[26:29], v185, s[36:37]
	global_load_dwordx4 v[30:33], v185, s[36:37] offset:64
	v_add_u32_e32 v145, 48, v114
	v_max_i32_e32 v145, 0, v145
	v_mad_u32_u24 v186, v145, s29, v0
	global_load_dwordx4 v[34:37], v186, s[36:37]
	global_load_dwordx4 v[38:41], v186, s[36:37] offset:64
	v_add_u32_e32 v145, 64, v114
	v_max_i32_e32 v145, 0, v145
	v_mad_u32_u24 v187, v145, s29, v0
	global_load_dwordx4 v[42:45], v187, s[36:37]
	global_load_dwordx4 v[46:49], v187, s[36:37] offset:64
	v_add_u32_e32 v145, 0x50, v114
	v_max_i32_e32 v145, 0, v145
	v_mad_u32_u24 v188, v145, s29, v0
	global_load_dwordx4 v[50:53], v188, s[36:37]
	global_load_dwordx4 v[54:57], v188, s[36:37] offset:64
	v_add_u32_e32 v145, 0x60, v114
	v_max_i32_e32 v145, 0, v145
	v_mad_u32_u24 v189, v145, s29, v0
	global_load_dwordx4 v[58:61], v189, s[36:37]
	global_load_dwordx4 v[62:65], v189, s[36:37] offset:64
	v_add_u32_e32 v145, 0x70, v114
	v_max_i32_e32 v145, 0, v145
	v_mad_u32_u24 v190, v145, s29, v0
	global_load_dwordx4 v[66:69], v190, s[36:37]
	global_load_dwordx4 v[70:73], v190, s[36:37] offset:64
	v_add_u32_e32 v145, 0x80, v114
	v_max_i32_e32 v145, 0, v145
	v_mad_u32_u24 v191, v145, s29, v0
	global_load_dwordx4 v[74:77], v191, s[36:37]
	global_load_dwordx4 v[78:81], v191, s[36:37] offset:64
	v_add_u32_e32 v211, s28, v160
	v_lshlrev_b32_e32 v165, 3, v205
	v_max_i32_e32 v145, 0, v211
	v_lshl_add_u32 v236, v145, 7, v165
	v_add_u32_e32 v145, 16, v211
	v_max_i32_e32 v145, 0, v145
	v_lshl_add_u32 v237, v145, 7, v165
	global_load_dwordx2 v[82:83], v236, s[38:39]
	global_load_dwordx2 v[84:85], v237, s[38:39]
	global_load_dwordx2 v[86:87], v236, s[38:39] offset:128
	global_load_dwordx2 v[88:89], v237, s[38:39] offset:128
	global_load_dwordx2 v[90:91], v236, s[38:39] offset:256
	global_load_dwordx2 v[92:93], v237, s[38:39] offset:256
	global_load_dwordx2 v[94:95], v236, s[38:39] offset:384
	global_load_dwordx2 v[96:97], v237, s[38:39] offset:384
	v_add_u32_e32 v145, 32, v211
	v_max_i32_e32 v145, 0, v145
	v_lshl_add_u32 v238, v145, 7, v165
	v_add_u32_e32 v145, 48, v211
	v_max_i32_e32 v145, 0, v145
	v_lshl_add_u32 v239, v145, 7, v165
	global_load_dwordx2 v[98:99], v238, s[38:39]
	global_load_dwordx2 v[100:101], v239, s[38:39]
	global_load_dwordx2 v[102:103], v238, s[38:39] offset:128
	global_load_dwordx2 v[104:105], v239, s[38:39] offset:128
	global_load_dwordx2 v[106:107], v238, s[38:39] offset:256
	global_load_dwordx2 v[108:109], v239, s[38:39] offset:256
	global_load_dwordx2 v[110:111], v238, s[38:39] offset:384
	global_load_dwordx2 v[112:113], v239, s[38:39] offset:384
	v_add_u32_e32 v145, 64, v211
	v_max_i32_e32 v145, 0, v145
	v_lshl_add_u32 v240, v145, 7, v165
	v_add_u32_e32 v145, 0x50, v211
	v_max_i32_e32 v145, 0, v145
	v_lshl_add_u32 v241, v145, 7, v165
	global_load_dwordx2 v[116:117], v240, s[38:39]
	global_load_dwordx2 v[118:119], v241, s[38:39]
	global_load_dwordx2 v[120:121], v240, s[38:39] offset:128
	global_load_dwordx2 v[122:123], v241, s[38:39] offset:128
	global_load_dwordx2 v[124:125], v240, s[38:39] offset:256
	global_load_dwordx2 v[126:127], v241, s[38:39] offset:256
	global_load_dwordx2 v[128:129], v240, s[38:39] offset:384
	global_load_dwordx2 v[130:131], v241, s[38:39] offset:384
	v_add_u32_e32 v145, 0x60, v211
	v_max_i32_e32 v145, 0, v145
	v_lshl_add_u32 v242, v145, 7, v165
	v_add_u32_e32 v145, 0x70, v211
	v_max_i32_e32 v145, 0, v145
	v_lshl_add_u32 v243, v145, 7, v165
	global_load_dwordx2 v[132:133], v242, s[38:39]
	global_load_dwordx2 v[134:135], v243, s[38:39]
	global_load_dwordx2 v[136:137], v242, s[38:39] offset:128
	global_load_dwordx2 v[138:139], v243, s[38:39] offset:128
	global_load_dwordx2 v[140:141], v242, s[38:39] offset:256
	global_load_dwordx2 v[142:143], v243, s[38:39] offset:256
	global_load_dwordx2 v[166:167], v242, s[38:39] offset:384
	global_load_dwordx2 v[168:169], v243, s[38:39] offset:384
	v_add_u32_e32 v145, 0x80, v211
	v_max_i32_e32 v145, 0, v145
	v_lshl_add_u32 v244, v145, 7, v165
	global_load_dwordx2 v[170:171], v244, s[38:39]
	v_mov_b32_e32 v172, 0
	v_mov_b32_e32 v173, 0
	global_load_dwordx2 v[174:175], v244, s[38:39] offset:128
	v_mov_b32_e32 v176, 0
	v_mov_b32_e32 v177, 0
	global_load_dwordx2 v[212:213], v244, s[38:39] offset:256
	v_mov_b32_e32 v214, 0
	v_mov_b32_e32 v215, 0
	global_load_dwordx2 v[216:217], v244, s[38:39] offset:384
	v_mov_b32_e32 v218, 0
	v_mov_b32_e32 v219, 0
	v_sub_u32_e32 v178, v205, v160
	v_cmp_ge_i32_e64 s[42:43], 0, v178
	v_cmp_ge_i32_e64 s[44:45], 1, v178
	v_cmp_ge_i32_e64 s[46:47], 2, v178
	v_cmp_ge_i32_e64 s[48:49], 3, v178
	s_waitcnt vmcnt(53)
	v_mfma_f32_16x16x32_bf16 v[10:13], v[10:13], v[2:5], 0
	s_waitcnt vmcnt(52)
	v_mfma_f32_16x16x32_bf16 v[10:13], v[14:17], v[6:9], v[10:13]
	s_waitcnt vmcnt(51)
	v_mfma_f32_16x16x32_bf16 v[18:21], v[18:21], v[2:5], 0
	s_waitcnt vmcnt(50)
	v_mfma_f32_16x16x32_bf16 v[18:21], v[22:25], v[6:9], v[18:21]
	s_waitcnt vmcnt(49)
	v_mfma_f32_16x16x32_bf16 v[26:29], v[26:29], v[2:5], 0
	s_waitcnt vmcnt(48)
	v_mfma_f32_16x16x32_bf16 v[26:29], v[30:33], v[6:9], v[26:29]
	s_waitcnt vmcnt(47)
	v_mfma_f32_16x16x32_bf16 v[34:37], v[34:37], v[2:5], 0
	s_waitcnt vmcnt(46)
	v_mfma_f32_16x16x32_bf16 v[34:37], v[38:41], v[6:9], v[34:37]
	s_waitcnt vmcnt(45)
	v_mfma_f32_16x16x32_bf16 v[42:45], v[42:45], v[2:5], 0
	s_waitcnt vmcnt(44)
	v_mfma_f32_16x16x32_bf16 v[42:45], v[46:49], v[6:9], v[42:45]
	s_waitcnt vmcnt(43)
	v_mfma_f32_16x16x32_bf16 v[50:53], v[50:53], v[2:5], 0
	s_waitcnt vmcnt(42)
	v_mfma_f32_16x16x32_bf16 v[50:53], v[54:57], v[6:9], v[50:53]
	s_waitcnt vmcnt(41)
	v_mfma_f32_16x16x32_bf16 v[58:61], v[58:61], v[2:5], 0
	s_waitcnt vmcnt(40)
	v_mfma_f32_16x16x32_bf16 v[58:61], v[62:65], v[6:9], v[58:61]
	s_waitcnt vmcnt(39)
	v_mfma_f32_16x16x32_bf16 v[66:69], v[66:69], v[2:5], 0
	s_waitcnt vmcnt(38)
	v_mfma_f32_16x16x32_bf16 v[66:69], v[70:73], v[6:9], v[66:69]
	s_waitcnt vmcnt(37)
	v_mfma_f32_16x16x32_bf16 v[74:77], v[74:77], v[2:5], 0
	s_waitcnt vmcnt(36)
	v_mfma_f32_16x16x32_bf16 v[74:77], v[78:81], v[6:9], v[74:77]
	s_cmp_ge_i32 s6, 8
	s_cbranch_scc1 .Ldil_m_fast
	v_mov_b32_e32 v10, v201
	v_mov_b32_e32 v11, v201
	v_mov_b32_e32 v12, v201
	v_mov_b32_e32 v13, v201
	s_cmp_ge_i32 s6, 7
	s_cselect_b64 vcc, -1, 0
	v_cndmask_b32_e32 v18, v201, v18, vcc
	v_cndmask_b32_e32 v19, v201, v19, vcc
	v_cndmask_b32_e32 v20, v201, v20, vcc
	v_cndmask_b32_e32 v21, v201, v21, vcc
	s_cmp_ge_i32 s6, 6
	s_cselect_b64 vcc, -1, 0
	v_cndmask_b32_e32 v26, v201, v26, vcc
	v_cndmask_b32_e32 v27, v201, v27, vcc
	v_cndmask_b32_e32 v28, v201, v28, vcc
	v_cndmask_b32_e32 v29, v201, v29, vcc
	s_cmp_ge_i32 s6, 5
	s_cselect_b64 vcc, -1, 0
	v_cndmask_b32_e32 v34, v201, v34, vcc
	v_cndmask_b32_e32 v35, v201, v35, vcc
	v_cndmask_b32_e32 v36, v201, v36, vcc
	v_cndmask_b32_e32 v37, v201, v37, vcc
	s_cmp_ge_i32 s6, 4
	s_cselect_b64 vcc, -1, 0
	v_cndmask_b32_e32 v42, v201, v42, vcc
	v_cndmask_b32_e32 v43, v201, v43, vcc
	v_cndmask_b32_e32 v44, v201, v44, vcc
	v_cndmask_b32_e32 v45, v201, v45, vcc
	s_cmp_ge_i32 s6, 3
	s_cselect_b64 vcc, -1, 0
	v_cndmask_b32_e32 v50, v201, v50, vcc
	v_cndmask_b32_e32 v51, v201, v51, vcc
	v_cndmask_b32_e32 v52, v201, v52, vcc
	v_cndmask_b32_e32 v53, v201, v53, vcc
	s_cmp_ge_i32 s6, 2
	s_cselect_b64 vcc, -1, 0
	v_cndmask_b32_e32 v58, v201, v58, vcc
	v_cndmask_b32_e32 v59, v201, v59, vcc
	v_cndmask_b32_e32 v60, v201, v60, vcc
	v_cndmask_b32_e32 v61, v201, v61, vcc
	s_cmp_ge_i32 s6, 1
	s_cselect_b64 vcc, -1, 0
	v_cndmask_b32_e32 v66, v201, v66, vcc
	v_cndmask_b32_e32 v67, v201, v67, vcc
	v_cndmask_b32_e32 v68, v201, v68, vcc
	v_cndmask_b32_e32 v69, v201, v69, vcc
	s_branch .Ldil_m_join

.LBB0_1055:
	s_or_b64 exec, exec, s[28:29]
	s_bitcmp1_b32 s27, 0
	s_cbranch_scc1 .Ldil2_done
	s_add_i32 s27, s27, 1
	s_branch .Ldil2_loop
.Ldil2_done:
.LBB0_1056:
	s_mov_b64 s[6:7], 0
